# prep phase covers prompt chunks only (32 items per WG); the 192 non-scan WGs re-enter the prep code after the grid barrier for the prep items of the sample sequences they scan themselves
# baseline (speedup 1.0000x reference)
; __device__ __forceinline__ bf16_t f2bf(float f) { return (bf16_t)(pk_bf16(f, 0.f) & 0xffffu); }
; __device__ __forceinline__ void phase_prep(const Params& p, unsigned char* shm) {
;     ...
;     {
;         const int tid0 = threadIdx.x, hh = blockIdx.x & 15;
; #pragma unroll
;         for (int i = 0; i < 4; ++i) { const int pc = tid0 + 512 * i, mat = pc >> 10, ii = (pc >> 4) & 63, s4 = pc & 15;
;             const f32x4 w = *(const f32x4*)((mat ? p.a2 : p.w2) + (size_t)ii * 1024 + hh * 64 + 4 * s4); bf16_t* d = (mat ? a2P : w2P) + (4 * s4) * LD + ii;
;             d[0] = f2bf(w[0]); d[LD] = f2bf(w[1]); d[2 * LD] = f2bf(w[2]); d[3 * LD] = f2bf(w[3]); }
;         if (tid0 < 64) { const int c = hh * 64 + tid0;
;             prm[tid0] = p.w0[c]; prm[64 + tid0] = p.a0[c]; prm[128 + tid0] = p.mu[c]; prm[192 + tid0] = p.mu[1024 + c]; prm[256 + tid0] = p.mu[2048 + c];
;             prm[320 + tid0] = p.k_k[c]; prm[384 + tid0] = p.k_a[c]; prm[448 + tid0] = p.r_k[c]; prm[512 + tid0] = p.mu[3072 + tid0]; prm[576 + tid0] = p.mu[3136 + tid0]; }
.LBB0_149:
	s_or_b64 exec, exec, s[2:3]
	s_movk_i32 s32, 0x2000
	s_movk_i32 s77, 0x100
.Lprep_re:
	s_add_i32 s5, 0, 0x20000
	s_movk_i32 s2, 0x200
	s_add_i32 s7, 0, 0x22400
	v_mov_b32_e32 v20, s7
	v_mov_b32_e32 v0, s5
	v_cmp_gt_u32_e32 vcc, s2, v133
	v_mov_b32_e32 v1, 0
	v_mov_b32_e32 v2, 0x68
	v_cndmask_b32_e32 v21, v20, v0, vcc
	v_mov_b32_e32 v0, 0x78
	v_cndmask_b32_e32 v2, v0, v2, vcc
	v_mov_b32_e32 v3, v1
	s_barrier
	s_lshl_b32 s4, s40, 6
	v_lshl_add_u64 v[2:3], s[0:1], 0, v[2:3]
	global_load_dwordx2 v[16:17], v[2:3], off
	s_load_dwordx2 s[2:3], s[0:1], 0x68
	s_load_dwordx2 s[8:9], s[0:1], 0x78
	v_lshrrev_b32_e32 v123, 4, v133
	v_add_u32_e32 v2, 0x200, v133
	v_writelane_b32 v244, s4, 8
	s_and_b32 s4, s4, 0x3c0
	v_lshlrev_b32_e32 v0, 12, v123
	v_bfe_u32 v22, v2, 4, 6
	v_xor_b32_e32 v23, 32, v123
	v_and_b32_e32 v3, 60, v134
	s_mov_b32 s11, 0
	s_lshl_b32 s10, s4, 2
	s_waitcnt lgkmcnt(0)
	v_lshl_add_u64 v[4:5], s[2:3], 0, v[0:1]
	v_lshl_add_u64 v[8:9], s[8:9], 0, v[0:1]
	v_mov_b32_e32 v19, v1
	v_lshlrev_b32_e32 v18, 12, v22
	v_lshlrev_b32_e32 v0, 12, v23
	v_lshlrev_b32_e32 v120, 2, v3
	v_mov_b32_e32 v121, v1
	v_lshl_add_u64 v[4:5], v[4:5], 0, s[10:11]
	v_lshl_add_u64 v[12:13], s[8:9], 0, v[0:1]
	v_lshl_add_u64 v[4:5], v[4:5], 0, v[120:121]
	v_lshl_add_u64 v[8:9], v[8:9], 0, s[10:11]
	v_lshl_add_u64 v[12:13], v[12:13], 0, s[10:11]
	global_load_dwordx4 v[4:7], v[4:5], off
	v_lshl_add_u64 v[8:9], v[8:9], 0, v[120:121]
	v_lshl_add_u64 v[12:13], v[12:13], 0, v[120:121]
	global_load_dwordx4 v[8:11], v[8:9], off
	v_mul_u32_u24_e32 v0, 0x90, v3
	global_load_dwordx4 v[12:15], v[12:13], off
	v_lshlrev_b32_e32 v24, 1, v123
	s_movk_i32 s2, 0x90
	v_add3_u32 v25, s5, v0, v24
	v_lshlrev_b32_e32 v22, 1, v22
	v_mad_u32_u24 v3, v3, s2, v20
	v_add3_u32 v0, v21, v0, v22
	v_cmp_gt_u32_e32 vcc, 64, v133
	v_add_u32_e32 v20, v3, v24
	v_lshl_add_u32 v3, v23, 1, v3
	s_waitcnt vmcnt(3)
	v_lshl_add_u64 v[16:17], v[16:17], 0, v[18:19]
	v_lshl_add_u64 v[16:17], v[16:17], 0, s[10:11]
	v_lshl_add_u64 v[16:17], v[16:17], 0, v[120:121]
	global_load_dwordx4 v[16:19], v[16:17], off
	s_waitcnt vmcnt(3)
	v_cvt_pk_bf16_f32 v4, v4, s0
	v_cvt_pk_bf16_f32 v5, v5, s0
	v_cvt_pk_bf16_f32 v6, v6, s0
	v_cvt_pk_bf16_f32 v7, v7, s0
	ds_write_b16 v25, v4
	ds_write_b16 v25, v5 offset:144
	ds_write_b16 v25, v6 offset:288
	ds_write_b16 v25, v7 offset:432
	s_waitcnt vmcnt(1)
	v_cvt_pk_bf16_f32 v4, v12, s0
	v_cvt_pk_bf16_f32 v8, v8, s0
	v_cvt_pk_bf16_f32 v9, v9, s0
	v_cvt_pk_bf16_f32 v10, v10, s0
	v_cvt_pk_bf16_f32 v11, v11, s0
	v_cvt_pk_bf16_f32 v5, v13, s0
	v_cvt_pk_bf16_f32 v6, v14, s0
	v_cvt_pk_bf16_f32 v7, v15, s0
	s_waitcnt vmcnt(0)
	v_cvt_pk_bf16_f32 v12, v16, s0
	v_cvt_pk_bf16_f32 v13, v17, s0
	v_cvt_pk_bf16_f32 v14, v18, s0
	v_cvt_pk_bf16_f32 v15, v19, s0
	ds_write_b16 v0, v12
	ds_write_b16 v0, v13 offset:144
	ds_write_b16 v0, v14 offset:288
	ds_write_b16 v0, v15 offset:432
	ds_write_b16 v20, v8
	ds_write_b16 v20, v9 offset:144
	ds_write_b16 v20, v10 offset:288
	ds_write_b16 v20, v11 offset:432
	ds_write_b16 v3, v4
	ds_write_b16 v3, v5 offset:144
	ds_write_b16 v3, v6 offset:288
	ds_write_b16 v3, v7 offset:432
	s_and_saveexec_b64 s[2:3], vcc
	s_cbranch_execz .LBB0_151
	s_load_dwordx4 s[8:11], s[0:1], 0x58
	s_load_dwordx2 s[16:17], s[0:1], 0x70
	s_load_dwordx4 s[12:15], s[0:1], 0x80
	s_load_dwordx2 s[18:19], s[0:1], 0x90
	v_or_b32_e32 v0, s4, v133
	v_lshlrev_b32_e32 v0, 2, v0
	s_waitcnt lgkmcnt(0)
	v_lshl_add_u64 v[4:5], s[8:9], 0, v[0:1]
	s_movk_i32 s6, 0x2000
	v_add_co_u32_e32 v4, vcc, s6, v4
	v_mov_b32_e32 v135, v1
	global_load_dword v3, v0, s[10:11]
	global_load_dword v6, v0, s[16:17]
	global_load_dword v7, v0, s[12:13]
	global_load_dword v8, v0, s[14:15]
	global_load_dword v9, v0, s[18:19]
	global_load_dword v10, v0, s[8:9]
	v_addc_co_u32_e32 v5, vcc, 0, v5, vcc
	v_lshl_add_u64 v[0:1], s[8:9], 0, v[134:135]
	v_add_co_u32_e32 v0, vcc, 0x3000, v0
	global_load_dword v11, v[4:5], off offset:-4096
	global_load_dword v12, v[4:5], off
	v_addc_co_u32_e32 v1, vcc, 0, v1, vcc
	global_load_dword v4, v[0:1], off
	global_load_dword v5, v[0:1], off offset:256
	v_add_u32_e32 v0, 0, v134
	v_add_u32_e32 v0, 0x24800, v0
	s_waitcnt vmcnt(8)
	ds_write2st64_b32 v0, v3, v6 offset1:1
	s_waitcnt vmcnt(3)
	ds_write2st64_b32 v0, v10, v11 offset0:2 offset1:3
	s_waitcnt vmcnt(2)
	ds_write2st64_b32 v0, v12, v7 offset0:4 offset1:5
	ds_write2st64_b32 v0, v8, v9 offset0:6 offset1:7
	s_waitcnt vmcnt(0)
	ds_write2st64_b32 v0, v4, v5 offset0:8 offset1:9

; __device__ __forceinline__ void phase_prep(const Params& p, unsigned char* shm) {
;     ...
;     u32x4 zpre[6]; int zcol[6], zrow[6], zlds[6];
;     {
;         const int t0 = threadIdx.x, hh0 = blockIdx.x & 15;
; #pragma unroll
;         for (int i = 0; i < 6; ++i) { int pc = t0 + 512 * i; const bool ok = pc < 2600; pc = ok ? pc : 2599;
;             const bool isH = pc < 1040; const int q = isH ? pc : pc - 1040, r = isH ? q >> 4 : q / 24, rem = isH ? q & 15 : q % 24;
;             zcol[i] = isH ? 3072 + 8 * rem : (rem >> 3) * 1024 + hh0 * 64 + 8 * (rem & 7); zrow[i] = r;
;             zlds[i] = ok ? (isH ? 36864 + (r * LZH + 8 * rem) * 2 : 36864 + 65 * LZH * 2 + (r * LZS + (rem >> 3) * 64 + 8 * (rem & 7)) * 2) : -1; }
;     }
;     auto zload = [&](int it) {
;         const int rw0 = (it >> 4) * 64;
; #pragma unroll
;         for (int i = 0; i < 6; ++i) { int grow = rw0 - 1 + zrow[i]; grow = grow < 0 ? 0 : grow; zpre[i] = *(const u32x4*)(p.Z + (size_t)grow * LDZ + ZC_S + zcol[i]); }
;     };
;     if ((int)blockIdx.x < NCH * 16) zload(blockIdx.x);
.LBB0_169:
	s_or_b64 exec, exec, s[2:3]
	v_or_b32_e32 v2, 0x800, v133
	s_movk_i32 s2, 0xa28
	v_add_u16_e32 v3, 0x3f0, v133
	v_mov_b32_e32 v4, 0x617
	v_cmp_gt_u32_e64 s[8:9], s2, v2
	s_movk_i32 s2, 0xaab
	v_mov_b32_e32 v172, -1
	v_cndmask_b32_e64 v2, v4, v3, s[8:9]
	v_mul_u32_u24_sdwa v157, v2, s2 dst_sel:DWORD dst_unused:UNUSED_PAD src0_sel:WORD_0 src1_sel:DWORD
	v_mov_b32_e32 v4, 24
	v_mul_lo_u16_sdwa v3, v157, v4 dst_sel:DWORD dst_unused:UNUSED_PAD src0_sel:WORD_1 src1_sel:DWORD
	v_sub_u16_e32 v2, v2, v3
	v_lshlrev_b32_e32 v5, 3, v2
	v_and_b32_e32 v3, 56, v5
	v_mov_b32_e32 v173, -1
	s_and_saveexec_b64 s[2:3], s[8:9]
	s_movk_i32 s6, 0xc8
	v_mul_u32_u24_sdwa v6, v157, s6 dst_sel:DWORD dst_unused:UNUSED_PAD src0_sel:WORD_1 src1_sel:DWORD
	v_and_b32_e32 v5, 0xc0, v5
	v_add3_u32 v5, v5, v6, v3
	v_mov_b32_e32 v6, 0xd510
	v_lshl_add_u32 v173, v5, 1, v6
	s_or_b64 exec, exec, s[2:3]
	v_min_u32_e32 v5, 39, v133
	v_add_u16_e32 v5, 0x5f0, v5
	v_mul_u32_u24_e32 v174, 0xaab, v5
	v_mul_lo_u16_sdwa v4, v174, v4 dst_sel:DWORD dst_unused:UNUSED_PAD src0_sel:WORD_1 src1_sel:DWORD
	v_sub_u16_e32 v4, v5, v4
	v_lshlrev_b32_e32 v6, 3, v4
	v_cmp_gt_u32_e64 s[8:9], 40, v133
	v_and_b32_e32 v5, 56, v6
	s_and_saveexec_b64 s[2:3], s[8:9]
	s_movk_i32 s6, 0xc8
	v_mul_u32_u24_sdwa v7, v174, s6 dst_sel:DWORD dst_unused:UNUSED_PAD src0_sel:WORD_1 src1_sel:DWORD
	v_and_b32_e32 v6, 0xc0, v6
	v_add3_u32 v6, v6, v7, v5
	v_mov_b32_e32 v7, 0xd510
	v_lshl_add_u32 v172, v6, 1, v7
	s_or_b64 exec, exec, s[2:3]
	v_lshlrev_b32_e32 v4, 7, v4
	v_and_b32_e32 v4, 0xc00, v4
	v_or3_b32 v26, s4, v4, v5
	v_add_u16_e32 v4, 0x1f0, v133
	v_mul_u32_u24_e32 v5, 0xaab, v4
	v_lshrrev_b32_e32 v175, 16, v5
	v_mul_lo_u16_e32 v5, 24, v175
	v_sub_u16_e32 v4, v4, v5
	v_lshlrev_b32_e32 v5, 7, v4
	v_lshlrev_b32_e32 v31, 3, v4
	v_lshlrev_b32_e32 v2, 7, v2
	v_and_b32_e32 v5, 0xc00, v5
	v_and_b32_e32 v29, 56, v31
	v_and_b32_e32 v2, 0xc00, v2
	s_cmp_lt_i32 s40, s32
	v_or3_b32 v28, s4, v5, v29
	v_or3_b32 v30, s4, v2, v3
	v_cndmask_b32_e32 v176, v0, v1, vcc
	s_cselect_b64 s[2:3], -1, 0
	s_cmp_ge_i32 s40, s32
	v_ashrrev_i32_e32 v125, 31, v124
	s_cbranch_scc1 .LBB0_175
	s_load_dwordx2 s[8:9], s[0:1], 0xb8
	s_lshl_b32 s4, s40, 2
	s_andn2_b32 s4, s4, 63
	s_add_i32 s4, s4, -1
	v_add_u32_e32 v0, s4, v123
	v_max_i32_e32 v0, 0, v0
	s_movk_i32 s6, 0x3a00
	s_waitcnt lgkmcnt(0)
	v_mov_b64_e32 v[8:9], s[8:9]
	v_mad_u64_u32 v[0:1], s[8:9], v0, s6, v[8:9]
	v_lshlrev_b32_e32 v10, 1, v122
	v_mov_b32_e32 v11, 0
	v_add_u32_e32 v2, s4, v176
	v_lshl_add_u64 v[0:1], v[0:1], 0, v[10:11]
	v_max_i32_e32 v2, 0, v2
	v_add_co_u32_e32 v0, vcc, 0x1000, v0
	v_mad_u64_u32 v[2:3], s[8:9], v2, s6, v[8:9]
	v_lshlrev_b32_e32 v10, 1, v24
	v_addc_co_u32_e32 v1, vcc, 0, v1, vcc
	v_lshl_add_u64 v[2:3], v[2:3], 0, v[10:11]
	v_add_co_u32_e32 v2, vcc, 0x1000, v2
	v_lshlrev_b32_e32 v10, 1, v28
	s_nop 0
	v_addc_co_u32_e32 v3, vcc, 0, v3, vcc
	global_load_dwordx4 v[20:23], v[0:1], off offset:2048
	global_load_dwordx4 v[16:19], v[2:3], off offset:2048
	v_add_u32_e32 v0, s4, v121
	v_max_i32_e32 v0, 0, v0
	v_mad_u64_u32 v[0:1], s[8:9], v0, s6, v[8:9]
	v_lshl_add_u64 v[0:1], v[124:125], 1, v[0:1]
	v_add_co_u32_e32 v12, vcc, 0x1000, v0
	v_add_u32_e32 v0, s4, v175
	v_max_i32_e32 v0, 0, v0
	v_addc_co_u32_e32 v13, vcc, 0, v1, vcc
	v_mad_u64_u32 v[0:1], s[8:9], v0, s6, v[8:9]
	v_lshl_add_u64 v[0:1], v[0:1], 0, v[10:11]
	v_add_u32_sdwa v10, s4, v157 dst_sel:DWORD dst_unused:UNUSED_PAD src0_sel:DWORD src1_sel:WORD_1
	v_add_co_u32_e32 v14, vcc, 0x1000, v0
	v_max_i32_e32 v10, 0, v10
	s_nop 0
	v_addc_co_u32_e32 v15, vcc, 0, v1, vcc
	global_load_dwordx4 v[4:7], v[12:13], off offset:2048
	global_load_dwordx4 v[0:3], v[14:15], off offset:2048
	v_mad_u64_u32 v[12:13], s[8:9], v10, s6, v[8:9]
	v_lshlrev_b32_e32 v10, 1, v30
	v_lshl_add_u64 v[12:13], v[12:13], 0, v[10:11]
	v_add_u32_sdwa v10, s4, v174 dst_sel:DWORD dst_unused:UNUSED_PAD src0_sel:DWORD src1_sel:WORD_1
	v_max_i32_e32 v10, 0, v10
	v_add_co_u32_e32 v32, vcc, 0x1000, v12
	v_mad_u64_u32 v[8:9], s[8:9], v10, s6, v[8:9]
	v_lshlrev_b32_e32 v10, 1, v26
	v_addc_co_u32_e32 v33, vcc, 0, v13, vcc
	v_lshl_add_u64 v[8:9], v[8:9], 0, v[10:11]
	v_add_co_u32_e32 v34, vcc, 0x1000, v8
	s_nop 1
	v_addc_co_u32_e32 v35, vcc, 0, v9, vcc
	global_load_dwordx4 v[12:15], v[32:33], off offset:2048
	global_load_dwordx4 v[8:11], v[34:35], off offset:2048
	s_movk_i32 s48, 0x110
	s_andn2_b64 vcc, exec, s[2:3]
	v_mul_u32_u24_e32 v135, 0x110, v123
	s_cbranch_vccz .LBB0_176
	s_branch .LBB0_280

; __device__ __forceinline__ unsigned pk_bf16(float lo, float hi) { const f32x2 v = (f32x2){lo, hi}; const bf16v2 b = __builtin_convertvector(v, bf16v2); return __builtin_bit_cast(unsigned, b); }
; __device__ __forceinline__ float bf_lo(unsigned u) { return __uint_as_float(u << 16); }
; __device__ __forceinline__ float bf_hi(unsigned u) { return __uint_as_float(u & 0xffff0000u); }
; #define LDS_BARRIER() do { asm volatile("s_waitcnt lgkmcnt(0)" ::: "memory"); __builtin_amdgcn_s_barrier(); asm volatile("" ::: "memory"); } while (0)
; __device__ __forceinline__ void phase_prep(const Params& p, unsigned char* shm) {
;     ...
;     auto zload = [&](int it) {
;         const int rw0 = (it >> 4) * 64;
; #pragma unroll
;         for (int i = 0; i < 6; ++i) { int grow = rw0 - 1 + zrow[i]; grow = grow < 0 ? 0 : grow; zpre[i] = *(const u32x4*)(p.Z + (size_t)grow * LDZ + ZC_S + zcol[i]); }
;     };
;     ...
;             const int nitem = item + (int)gridDim.x;
;             zload(nitem < NCH * 16 ? nitem : item);
;         }
;         LDS_BARRIER();
;         {
;             const int j = tid >> 3, p8 = tid & 7;
; #pragma unroll
;             for (int isa = 0; isa < 2; ++isa) {
;                 const int c = isa * 64 + 8 * p8;
;                 const u32x4 cu = *(const u32x4*)(zh + (j + 1) * LZH + c), pu = *(const u32x4*)(zh + j * LZH + c);
;                 const f32x4 m0 = *(const f32x4*)(prm + 512 + c), m1 = *(const f32x4*)(prm + 512 + c + 4);
;                 const unsigned cw[4] = {cu.x, cu.y, cu.z, cu.w}, pw[4] = {pu.x, pu.y, pu.z, pu.w};
;                 float x[8];
; #pragma unroll
;                 for (int e = 0; e < 4; ++e) { const float c0 = bf_lo(cw[e]), c1 = bf_hi(cw[e]), mA = e < 2 ? m0[2 * e] : m1[2 * e - 4], mB = e < 2 ? m0[2 * e + 1] : m1[2 * e - 3];
;                     x[2 * e] = c0 + mA * (bf_lo(pw[e]) - c0); x[2 * e + 1] = c1 + mB * (bf_hi(pw[e]) - c1); }
;                 if (isa == 0) {
; #pragma unroll
;                     for (int e = 0; e < 4; ++e) { const f32x2 th = tanh2((f32x2){x[2 * e], x[2 * e + 1]}); x[2 * e] = th.x; x[2 * e + 1] = th.y; }
;                 }
;                 *(u32x4*)((isa ? tha : thw) + j * LD + 8 * p8) = (u32x4){pk_bf16(x[0], x[1]), pk_bf16(x[2], x[3]), pk_bf16(x[4], x[5]), pk_bf16(x[6], x[7])};
.LBB0_189:
	s_or_b64 exec, exec, s[18:19]
	s_add_i32 s70, s26, s77
	s_cmp_ge_i32 s70, s32
	s_cselect_b64 s[42:43], -1, 0
	s_cmp_lt_i32 s70, s32
	s_cselect_b32 s18, s70, s26
	s_mov_b64 s[20:21], s[88:89]
	s_lshl_b32 s18, s18, 2
	s_andn2_b32 s18, s18, 63
	s_add_i32 s22, s18, -1
	v_add_u32_e32 v0, s22, v123
	v_max_i32_e32 v0, 0, v0
	s_mov_b64 s[18:19], s[90:91]
	s_waitcnt vmcnt(6) lgkmcnt(0)
	v_mov_b64_e32 v[8:9], s[20:21]
	v_mad_u64_u32 v[0:1], s[20:21], v0, s3, v[8:9]
	v_lshlrev_b32_e32 v126, 1, v122
	v_add_u32_e32 v2, s22, v176
	v_lshl_add_u64 v[0:1], v[0:1], 0, v[126:127]
	v_max_i32_e32 v2, 0, v2
	v_add_co_u32_e32 v0, vcc, s49, v0
	v_mad_u64_u32 v[2:3], s[20:21], v2, s3, v[8:9]
	v_mov_b32_e32 v137, v127
	v_addc_co_u32_e32 v1, vcc, 0, v1, vcc
	v_lshl_add_u64 v[2:3], v[2:3], 0, v[136:137]
	v_add_co_u32_e32 v2, vcc, s49, v2
	v_mov_b32_e32 v139, v127
	s_nop 0
	v_addc_co_u32_e32 v3, vcc, 0, v3, vcc
	global_load_dwordx4 v[20:23], v[0:1], off offset:2048
	global_load_dwordx4 v[16:19], v[2:3], off offset:2048
	v_add_u32_e32 v0, s22, v121
	v_max_i32_e32 v0, 0, v0
	v_mad_u64_u32 v[0:1], s[20:21], v0, s3, v[8:9]
	v_add_u32_e32 v2, s22, v175
	v_lshl_add_u64 v[0:1], v[124:125], 1, v[0:1]
	v_max_i32_e32 v2, 0, v2
	v_add_co_u32_e32 v0, vcc, s49, v0
	v_mad_u64_u32 v[2:3], s[20:21], v2, s3, v[8:9]
	v_add_u32_sdwa v10, s22, v157 dst_sel:DWORD dst_unused:UNUSED_PAD src0_sel:DWORD src1_sel:WORD_1
	v_addc_co_u32_e32 v1, vcc, 0, v1, vcc
	v_lshl_add_u64 v[2:3], v[2:3], 0, v[138:139]
	v_max_i32_e32 v10, 0, v10
	v_add_co_u32_e32 v2, vcc, s49, v2
	v_mad_u64_u32 v[10:11], s[20:21], v10, s3, v[8:9]
	v_mov_b32_e32 v141, v127
	v_add_u32_sdwa v12, s22, v174 dst_sel:DWORD dst_unused:UNUSED_PAD src0_sel:DWORD src1_sel:WORD_1
	v_addc_co_u32_e32 v3, vcc, 0, v3, vcc
	v_lshl_add_u64 v[10:11], v[10:11], 0, v[140:141]
	v_max_i32_e32 v12, 0, v12
	v_add_co_u32_e32 v10, vcc, s49, v10
	v_mad_u64_u32 v[8:9], s[20:21], v12, s3, v[8:9]
	v_mov_b32_e32 v143, v127
	v_lshlrev_b32_e32 v188, 3, v187
	v_addc_co_u32_e32 v11, vcc, 0, v11, vcc
	v_lshl_add_u64 v[8:9], v[8:9], 0, v[142:143]
	v_ashrrev_i32_e32 v186, 3, v187
	v_and_b32_e32 v32, 56, v188
	v_add_co_u32_e32 v8, vcc, s49, v8
	v_mul_u32_u24_e32 v24, s48, v186
	s_nop 0
	v_addc_co_u32_e32 v9, vcc, 0, v9, vcc
	v_lshlrev_b32_e32 v144, 1, v32
	global_load_dwordx4 v[4:7], v[0:1], off offset:2048
	s_nop 0
	global_load_dwordx4 v[0:3], v[2:3], off offset:2048
	s_nop 0
	global_load_dwordx4 v[12:15], v[10:11], off offset:2048
	s_nop 0
	global_load_dwordx4 v[8:11], v[8:9], off offset:2048
	s_waitcnt lgkmcnt(0)
	s_barrier
	v_add3_u32 v45, 0, v24, v144
	ds_read_b128 v[24:27], v45 offset:37136
	ds_read_b128 v[28:31], v45 offset:36864
	v_lshlrev_b32_e32 v46, 2, v32
	v_add_u32_e32 v32, 0, v46
	v_add_u32_e32 v47, 0x25000, v32
	ds_read_b128 v[32:35], v47
	ds_read_b128 v[36:39], v47 offset:16
	s_waitcnt lgkmcnt(3)
	v_lshlrev_b32_e32 v40, 16, v24
	v_and_b32_e32 v41, 0xffff0000, v24
	s_waitcnt lgkmcnt(2)
	v_lshlrev_b32_e32 v42, 16, v28
	v_and_b32_e32 v43, 0xffff0000, v28
	v_lshlrev_b32_e32 v24, 16, v25
	v_and_b32_e32 v25, 0xffff0000, v25
	v_lshlrev_b32_e32 v28, 16, v29
	v_and_b32_e32 v29, 0xffff0000, v29
	v_pk_add_f32 v[28:29], v[28:29], v[24:25] neg_lo:[0,1] neg_hi:[0,1]
	v_pk_add_f32 v[42:43], v[42:43], v[40:41] neg_lo:[0,1] neg_hi:[0,1]
	s_waitcnt lgkmcnt(1)
	v_pk_fma_f32 v[24:25], v[34:35], v[28:29], v[24:25]
	v_lshlrev_b32_e32 v28, 16, v26
	v_and_b32_e32 v29, 0xffff0000, v26
	v_lshlrev_b32_e32 v34, 16, v30
	v_and_b32_e32 v35, 0xffff0000, v30
	v_lshlrev_b32_e32 v26, 16, v27
	v_and_b32_e32 v27, 0xffff0000, v27
	v_lshlrev_b32_e32 v30, 16, v31
	v_and_b32_e32 v31, 0xffff0000, v31
	v_pk_add_f32 v[34:35], v[34:35], v[28:29] neg_lo:[0,1] neg_hi:[0,1]
	v_pk_add_f32 v[30:31], v[30:31], v[26:27] neg_lo:[0,1] neg_hi:[0,1]
	v_pk_fma_f32 v[32:33], v[32:33], v[42:43], v[40:41]
	s_waitcnt lgkmcnt(0)
	v_pk_fma_f32 v[28:29], v[36:37], v[34:35], v[28:29]
	v_pk_fma_f32 v[26:27], v[38:39], v[30:31], v[26:27]
	v_pk_mul_f32 v[32:33], v[32:33], s[2:3] op_sel_hi:[1,0]
	v_pk_mul_f32 v[24:25], v[24:25], s[2:3] op_sel_hi:[1,0]
	v_pk_mul_f32 v[28:29], v[28:29], s[2:3] op_sel_hi:[1,0]
	v_pk_mul_f32 v[26:27], v[26:27], s[2:3] op_sel_hi:[1,0]
	v_exp_f32_e32 v32, v32
	v_exp_f32_e32 v33, v33
	v_exp_f32_e32 v24, v24
	v_exp_f32_e32 v25, v25
	v_exp_f32_e32 v28, v28
	v_exp_f32_e32 v29, v29
	v_exp_f32_e32 v26, v26
	v_exp_f32_e32 v27, v27
	v_pk_add_f32 v[32:33], v[32:33], 1.0 op_sel_hi:[1,0]
	v_pk_add_f32 v[24:25], v[24:25], 1.0 op_sel_hi:[1,0]
	v_pk_add_f32 v[28:29], v[28:29], 1.0 op_sel_hi:[1,0]
	v_pk_add_f32 v[26:27], v[26:27], 1.0 op_sel_hi:[1,0]
	v_rcp_f32_e32 v32, v32
	v_rcp_f32_e32 v33, v33
	v_rcp_f32_e32 v24, v24
	v_rcp_f32_e32 v25, v25
	v_rcp_f32_e32 v28, v28
	v_rcp_f32_e32 v29, v29
	v_rcp_f32_e32 v26, v26
	v_rcp_f32_e32 v27, v27
	v_mul_u32_u24_e32 v44, s50, v186
	v_pk_fma_f32 v[30:31], v[32:33], 2.0, 1.0 op_sel_hi:[1,0,0] neg_lo:[1,0,0] neg_hi:[1,0,0]
	v_pk_fma_f32 v[32:33], v[24:25], 2.0, 1.0 op_sel_hi:[1,0,0] neg_lo:[1,0,0] neg_hi:[1,0,0]
	v_pk_fma_f32 v[28:29], v[28:29], 2.0, 1.0 op_sel_hi:[1,0,0] neg_lo:[1,0,0] neg_hi:[1,0,0]
	v_pk_fma_f32 v[34:35], v[26:27], 2.0, 1.0 op_sel_hi:[1,0,0] neg_lo:[1,0,0] neg_hi:[1,0,0]
	v_cvt_pk_bf16_f32 v24, v30, v31
	v_cvt_pk_bf16_f32 v25, v32, v33
	v_cvt_pk_bf16_f32 v26, v28, v29
	v_cvt_pk_bf16_f32 v27, v34, v35
	v_add3_u32 v44, 0, v44, v144
	ds_read_b128 v[28:31], v45 offset:37264
	ds_write_b128 v44, v[24:27]
	ds_read_b128 v[24:27], v45 offset:36992
	ds_read_b128 v[32:35], v47 offset:256
	ds_read_b128 v[36:39], v47 offset:272
	s_and_b32 s22, s26, 15
	s_lshl_b32 s40, s22, 7
	s_waitcnt lgkmcnt(4)
; __device__ __forceinline__ float bf_lo(unsigned u) { return __uint_as_float(u << 16); }
; __device__ __forceinline__ void phase_prep(const Params& p, unsigned char* shm) {
;     ...
;                 if (isa == 0) {
; #pragma unroll
;                     for (int e = 0; e < 4; ++e) { const f32x2 th = tanh2((f32x2){x[2 * e], x[2 * e + 1]}); x[2 * e] = th.x; x[2 * e + 1] = th.y; }
;                 }
;                 *(u32x4*)((isa ? tha : thw) + j * LD + 8 * p8) = (u32x4){pk_bf16(x[0], x[1]), pk_bf16(x[2], x[3]), pk_bf16(x[4], x[5]), pk_bf16(x[6], x[7])};
;             }
;             {
;                 const u32x4 cu = *(const u32x4*)(zs + (j + 1) * LZS + 128 + 8 * p8), pu = *(const u32x4*)(zs + j * LZS + 128 + 8 * p8);
;                 const f32x4 m0 = *(const f32x4*)(prm + 256 + 8 * p8), m1 = *(const f32x4*)(prm + 256 + 8 * p8 + 4);
;                 const unsigned cw[4] = {cu.x, cu.y, cu.z, cu.w}, pw[4] = {pu.x, pu.y, pu.z, pu.w};
;                 float x[8];
; #pragma unroll
;                 for (int e = 0; e < 4; ++e) { const float c0 = bf_lo(cw[e]), c1 = bf_hi(cw[e]), mA = e < 2 ? m0[2 * e] : m1[2 * e - 4], mB = e < 2 ? m0[2 * e + 1] : m1[2 * e - 3];
;                     x[2 * e] = c0 + mA * (bf_lo(pw[e]) - c0); x[2 * e + 1] = c1 + mB * (bf_hi(pw[e]) - c1); }
;                 *(u32x4*)(p.PV + ((size_t)(row0 + j) * 16 + h) * 64 + 8 * p8) = (u32x4){pk_bf16(x[0], x[1]), pk_bf16(x[2], x[3]), pk_bf16(x[4], x[5]), pk_bf16(x[6], x[7])};
;             }
;         }
;         LDS_BARRIER();
;         const int tt = wid & 3, chh = wid >> 2, tk = 16 * tt + fr, row = row0 + tk;
;         f32x4 lw[2], av[2], vm[2], kkv[2], kp[2], rm[2], cs[2]; float nrm = 0.f, rk = 0.f;
;         {
;             f32x4 accd[2], acca[2];
; #pragma unroll
;             for (int n = 0; n < 2; ++n) { accd[n] = (f32x4){0.f, 0.f, 0.f, 0.f}; acca[n] = (f32x4){0.f, 0.f, 0.f, 0.f}; }
; #pragma unroll
;             for (int ks = 0; ks < 2; ++ks) {
;                 const bf16x8 bw = ldfrag(thw, LD, 16 * tt, 32 * ks, fr, fq), ba = ldfrag(tha, LD, 16 * tt, 32 * ks, fr, fq);
; #pragma unroll
;                 for (int n = 0; n < 2; ++n) {
;                     accd[n] = MFMA16(ldfrag(w2P, LD, 32 * chh + 16 * n, 32 * ks, fr, fq), bw, accd[n]);
;                     acca[n] = MFMA16(ldfrag(a2P, LD, 32 * chh + 16 * n, 32 * ks, fr, fq), ba, acca[n]);
;                 }
;             }
	v_lshlrev_b32_e32 v40, 16, v28
	v_and_b32_e32 v41, 0xffff0000, v28
	s_waitcnt lgkmcnt(2)
	v_lshlrev_b32_e32 v42, 16, v24
	v_and_b32_e32 v43, 0xffff0000, v24
	v_lshlrev_b32_e32 v28, 16, v29
	v_and_b32_e32 v29, 0xffff0000, v29
	v_lshlrev_b32_e32 v24, 16, v25
	v_and_b32_e32 v25, 0xffff0000, v25
	v_pk_add_f32 v[24:25], v[24:25], v[28:29] neg_lo:[0,1] neg_hi:[0,1]
	v_pk_add_f32 v[42:43], v[42:43], v[40:41] neg_lo:[0,1] neg_hi:[0,1]
	s_waitcnt lgkmcnt(1)
	v_pk_fma_f32 v[28:29], v[34:35], v[24:25], v[28:29]
	v_lshlrev_b32_e32 v24, 16, v30
	v_and_b32_e32 v25, 0xffff0000, v30
	v_lshlrev_b32_e32 v34, 16, v26
	v_and_b32_e32 v35, 0xffff0000, v26
	v_pk_add_f32 v[34:35], v[34:35], v[24:25] neg_lo:[0,1] neg_hi:[0,1]
	v_lshlrev_b32_e32 v26, 16, v27
	s_waitcnt lgkmcnt(0)
	v_pk_fma_f32 v[34:35], v[36:37], v[34:35], v[24:25]
	v_lshlrev_b32_e32 v24, 16, v31
	v_and_b32_e32 v25, 0xffff0000, v31
	v_and_b32_e32 v27, 0xffff0000, v27
	v_pk_add_f32 v[26:27], v[26:27], v[24:25] neg_lo:[0,1] neg_hi:[0,1]
	v_pk_fma_f32 v[32:33], v[32:33], v[42:43], v[40:41]
	v_pk_fma_f32 v[30:31], v[38:39], v[26:27], v[24:25]
	v_cvt_pk_bf16_f32 v24, v32, v33
	v_cvt_pk_bf16_f32 v25, v28, v29
	v_cvt_pk_bf16_f32 v26, v34, v35
	v_cvt_pk_bf16_f32 v27, v30, v31
	ds_write_b128 v44, v[24:27] offset:9216
	v_mul_u32_u24_e32 v24, s51, v186
	v_add3_u32 v28, 0, v24, v144
	ds_read_b128 v[24:27], v28 offset:55200
	ds_read_b128 v[28:31], v28 offset:54800
	v_add_u32_e32 v36, s52, v46
	ds_read_b128 v[32:35], v36
	ds_read_b128 v[36:39], v36 offset:16
	v_mov_b32_e32 v145, v127
	s_waitcnt lgkmcnt(3)
	v_lshlrev_b32_e32 v40, 16, v24
	v_and_b32_e32 v41, 0xffff0000, v24
	s_waitcnt lgkmcnt(2)
	v_lshlrev_b32_e32 v42, 16, v28
	v_and_b32_e32 v43, 0xffff0000, v28
	v_lshlrev_b32_e32 v24, 16, v25
	v_and_b32_e32 v25, 0xffff0000, v25
	v_lshlrev_b32_e32 v28, 16, v29
	v_and_b32_e32 v29, 0xffff0000, v29
	v_pk_add_f32 v[28:29], v[28:29], v[24:25] neg_lo:[0,1] neg_hi:[0,1]
	v_pk_add_f32 v[42:43], v[42:43], v[40:41] neg_lo:[0,1] neg_hi:[0,1]
	s_waitcnt lgkmcnt(1)
	v_pk_fma_f32 v[28:29], v[34:35], v[28:29], v[24:25]
	v_lshlrev_b32_e32 v24, 16, v26
	v_and_b32_e32 v25, 0xffff0000, v26
	v_lshlrev_b32_e32 v34, 16, v30
	v_and_b32_e32 v35, 0xffff0000, v30
	v_pk_add_f32 v[34:35], v[34:35], v[24:25] neg_lo:[0,1] neg_hi:[0,1]
	v_lshlrev_b32_e32 v26, 16, v31
	s_waitcnt lgkmcnt(0)
	v_pk_fma_f32 v[34:35], v[36:37], v[34:35], v[24:25]
	v_lshlrev_b32_e32 v24, 16, v27
	v_and_b32_e32 v25, 0xffff0000, v27
	v_and_b32_e32 v27, 0xffff0000, v31
	v_pk_add_f32 v[26:27], v[26:27], v[24:25] neg_lo:[0,1] neg_hi:[0,1]
	v_pk_fma_f32 v[32:33], v[32:33], v[42:43], v[40:41]
	v_pk_fma_f32 v[30:31], v[38:39], v[26:27], v[24:25]
	v_cvt_pk_bf16_f32 v25, v28, v29
	v_add_u32_e32 v28, s24, v186
	v_ashrrev_i32_e32 v29, 31, v28
	v_lshlrev_b64 v[28:29], 11, v[28:29]
	v_lshl_add_u64 v[28:29], s[18:19], 0, v[28:29]
	v_lshl_add_u64 v[28:29], v[28:29], 0, s[40:41]
	s_ashr_i32 s29, s25, 8
	v_and_b32_e32 v185, 15, v187
	v_cvt_pk_bf16_f32 v24, v32, v33
	v_cvt_pk_bf16_f32 v26, v34, v35
	v_cvt_pk_bf16_f32 v27, v30, v31
	v_lshl_add_u64 v[28:29], v[28:29], 0, v[144:145]
	s_lshl_b32 s18, s29, 5
	global_store_dwordx4 v[28:29], v[24:27], off
	v_and_b32_e32 v141, 48, v187
	s_waitcnt lgkmcnt(0)
	s_barrier
	v_or_b32_e32 v24, s18, v185
	v_mul_u32_u24_e32 v145, s50, v24
	v_add3_u32 v60, s5, v141, v145
	s_bfe_u32 s28, s25, 0x20006
	ds_read_b128 v[24:27], v60
	v_lshl_or_b32 v126, s28, 4, v185
	v_mad_u32_u24 v143, v126, s50, 0
	v_add_u32_e32 v189, v143, v141
	v_add3_u32 v64, s7, v141, v145
	ds_read_b128 v[28:31], v189
	ds_read_b128 v[32:35], v64
	ds_read_b128 v[36:39], v189 offset:64
	ds_read_b128 v[40:43], v60 offset:64
	ds_read_b128 v[44:47], v189 offset:9216
	ds_read_b128 v[48:51], v189 offset:9280
	ds_read_b128 v[52:55], v64 offset:64
	ds_read_b128 v[56:59], v60 offset:2304
	ds_read_b128 v[60:63], v60 offset:2368
	s_waitcnt lgkmcnt(4)
	v_mfma_f32_16x16x32_bf16 v[32:35], v[32:35], v[44:47], 0
	v_bfe_u32 v137, v187, 4, 2
	v_lshlrev_b32_e32 v139, 2, v137
	v_or_b32_e32 v146, s18, v139
	v_mfma_f32_16x16x32_bf16 v[24:27], v[24:27], v[28:31], 0
	v_lshlrev_b32_e32 v147, 1, v146
	s_lshl_b32 s20, s28, 8
	s_add_i32 s20, s20, 0
	s_waitcnt lgkmcnt(1)
	v_mfma_f32_16x16x32_bf16 v[28:31], v[56:59], v[28:31], 0
	ds_read_b128 v[56:59], v64 offset:2304
	ds_read_b128 v[64:67], v64 offset:2368
	s_add_i32 s20, s20, 0x1b400
	v_cmp_eq_u32_e64 s[18:19], 15, v185
	v_mfma_f32_16x16x32_bf16 v[72:75], v[52:55], v[48:51], v[32:35]
	v_lshl_add_u32 v191, v146, 2, s20
	s_nop 1
	v_lshlrev_b32_e32 v34, 2, v146
	v_add_u32_e32 v35, 0, v34
	v_mfma_f32_16x16x32_bf16 v[40:43], v[40:43], v[36:39], v[24:27]
	v_add_u32_e32 v32, 0x24900, v35
	ds_read_b128 v[84:87], v32
	s_waitcnt lgkmcnt(3)
	v_mfma_f32_16x16x32_bf16 v[24:27], v[60:63], v[36:39], v[28:31]
	v_lshlrev_b32_e32 v36, 8, v126
	s_nop 1
	v_add_u32_e32 v28, 0x24800, v35
	ds_read_b128 v[28:31], v28
	s_waitcnt lgkmcnt(3)
	v_mfma_f32_16x16x32_bf16 v[44:47], v[56:59], v[44:47], 0
	s_waitcnt lgkmcnt(0)
; __device__ __forceinline__ void phase_prep(const Params& p, unsigned char* shm) {
;     ...
;             const bf16_t* zc = zs + (tk + 1) * LZS; const bf16_t* zp = zs + tk * LZS;
; #pragma unroll
;             for (int n = 0; n < 2; ++n) {
;                 const int c4 = 32 * chh + 16 * n + 4 * fq;
;                 const f32x4 d = *(const f32x4*)(prm + c4) + accd[n], al = *(const f32x4*)(prm + 64 + c4) + acca[n];
; { const f32x2 s0 = sigmoid2((f32x2){d[0], d[1]}), s1 = sigmoid2((f32x2){d[2], d[3]}), a0 = sigmoid2((f32x2){al[0], al[1]}), a1 = sigmoid2((f32x2){al[2], al[3]});
;                   lw[n] = (f32x4){s0.x, s0.y, s1.x, s1.y} * (-0.87503886f); av[n] = (f32x4){a0.x, a0.y, a1.x, a1.y}; }
;                 { const f32x4 vc = ld_bf4(zc + 128 + c4), vp = ld_bf4(zp + 128 + c4); vm[n] = vc + *(const f32x4*)(prm + 256 + c4) * (vp - vc); }
;                 const f32x4 kc = ld_bf4(zc + 64 + c4), kpv = ld_bf4(zp + 64 + c4);
;                 const f32x4 k = kc + *(const f32x4*)(prm + 192 + c4) * (kpv - kc);
;                 kkv[n] = k * *(const f32x4*)(prm + 320 + c4);
;                 kp[n] = k * (1.0f + (av[n] - 1.0f) * *(const f32x4*)(prm + 384 + c4));
;                 const f32x4 rc = ld_bf4(zc + c4), rp = ld_bf4(zp + c4);
;                 rm[n] = rc + *(const f32x4*)(prm + 128 + c4) * (rp - rc);
;                 const f32x4 rkw = rm[n] * kp[n] * *(const f32x4*)(prm + 448 + c4);
;                 { const f32x4 sq = kkv[n] * kkv[n]; nrm += (sq[0] + sq[1]) + (sq[2] + sq[3]); }
;                 rk += rkw[0] + rkw[1] + rkw[2] + rkw[3];
; #pragma unroll
;                 for (int j = 0; j < 4; ++j) {
;                     float x = lw[n][j];
;                     x += __int_as_float(__builtin_amdgcn_update_dpp(0, __float_as_int(x), 0x111, 0xf, 0xf, false));
;                     x += __int_as_float(__builtin_amdgcn_update_dpp(0, __float_as_int(x), 0x112, 0xf, 0xf, false));
;                     x += __int_as_float(__builtin_amdgcn_update_dpp(0, __float_as_int(x), 0x114, 0xf, 0xf, false));
;                     x += __int_as_float(__builtin_amdgcn_update_dpp(0, __float_as_int(x), 0x118, 0xf, 0xf, false));
;                     cs[n][j] = x;
;                 }
;                 if (fr == 15) *(f32x4*)(tot + tt * 64 + c4) = cs[n];
	v_pk_add_f32 v[28:29], v[40:41], v[28:29]
	s_nop 0
	v_pk_mul_f32 v[28:29], v[28:29], s[4:5] op_sel_hi:[1,0]
	v_pk_add_f32 v[30:31], v[42:43], v[30:31]
	v_exp_f32_e32 v28, v28
	v_exp_f32_e32 v29, v29
	v_mfma_f32_16x16x32_bf16 v[56:59], v[64:67], v[48:51], v[44:47]
	v_mul_f32_e64 v30, v30, s4
	v_mul_f32_e64 v31, v31, s4
	v_pk_add_f32 v[28:29], v[28:29], 1.0 op_sel_hi:[1,0]
	s_nop 0
	v_rcp_f32_e32 v32, v28
	v_rcp_f32_e32 v33, v29
	v_add3_u32 v28, v143, v36, v147
	v_add_u32_e32 v28, 0xd000, v28
	v_add_u32_e32 v29, s52, v34
	v_add_u32_e32 v34, 0x24b00, v35
	ds_read2_b64 v[52:55], v28 offset0:228 offset1:244
	ds_read2_b64 v[48:51], v28 offset0:194 offset1:212
	ds_read2_b64 v[68:71], v28 offset0:162 offset1:178
	ds_read_b128 v[44:47], v29
	ds_read_b128 v[92:95], v34
	v_add_u32_e32 v29, 0x24d00, v35
	v_add_u32_e32 v34, 0x24e00, v35
	v_exp_f32_e32 v30, v30
	v_exp_f32_e32 v31, v31
	ds_read_b128 v[96:99], v29
	ds_read_b128 v[76:79], v34
	v_add_u32_e32 v29, 0x24a00, v35
	v_add_u32_e32 v34, 0x24f00, v35
	v_pk_mul_f32 v[154:155], v[32:33], s[6:7] op_sel_hi:[1,0]
	ds_read_b128 v[64:67], v29
	ds_read_b128 v[60:63], v34
	v_mov_b32_e32 v34, v127
	v_mov_b32_e32 v35, v127
	v_pk_add_f32 v[30:31], v[30:31], 1.0 op_sel_hi:[1,0]
	v_mov_b32_dpp v34, v154 row_shr:1 row_mask:0xf bank_mask:0xf
	v_mov_b32_dpp v35, v155 row_shr:1 row_mask:0xf bank_mask:0xf
	v_pk_fma_f32 v[32:33], v[32:33], s[6:7], v[34:35] op_sel_hi:[1,0,1]
	v_rcp_f32_e32 v30, v30
	v_rcp_f32_e32 v31, v31
	v_add_f32_dpp v32, v32, v32 row_shr:2 row_mask:0xf bank_mask:0xf bound_ctrl:1
	v_add_f32_dpp v33, v33, v33 row_shr:2 row_mask:0xf bank_mask:0xf bound_ctrl:1
	v_pk_mul_f32 v[152:153], v[30:31], s[6:7] op_sel_hi:[1,0]
	v_mov_b32_e32 v34, v127
	v_mov_b32_e32 v35, v127
	v_add_f32_dpp v32, v32, v32 row_shr:4 row_mask:0xf bank_mask:0xf bound_ctrl:1
	v_add_f32_dpp v33, v33, v33 row_shr:4 row_mask:0xf bank_mask:0xf bound_ctrl:1
	v_mov_b32_dpp v34, v152 row_shr:1 row_mask:0xf bank_mask:0xf
	v_mov_b32_dpp v35, v153 row_shr:1 row_mask:0xf bank_mask:0xf
	v_add_f32_dpp v40, v32, v32 row_shr:8 row_mask:0xf bank_mask:0xf bound_ctrl:1
	v_add_f32_dpp v41, v33, v33 row_shr:8 row_mask:0xf bank_mask:0xf bound_ctrl:1
	v_pk_fma_f32 v[30:31], v[30:31], s[6:7], v[34:35] op_sel_hi:[1,0,1]
	s_nop 1
	v_add_f32_dpp v30, v30, v30 row_shr:2 row_mask:0xf bank_mask:0xf bound_ctrl:1
	v_add_f32_dpp v31, v31, v31 row_shr:2 row_mask:0xf bank_mask:0xf bound_ctrl:1
	s_nop 0
	v_add_f32_dpp v30, v30, v30 row_shr:4 row_mask:0xf bank_mask:0xf bound_ctrl:1
	v_add_f32_dpp v31, v31, v31 row_shr:4 row_mask:0xf bank_mask:0xf bound_ctrl:1
	s_nop 0
	v_add_f32_dpp v42, v30, v30 row_shr:8 row_mask:0xf bank_mask:0xf bound_ctrl:1
	v_add_f32_dpp v43, v31, v31 row_shr:8 row_mask:0xf bank_mask:0xf bound_ctrl:1
	s_and_saveexec_b64 s[20:21], s[18:19]
	ds_write_b128 v191, v[40:43]
	s_or_b64 exec, exec, s[20:21]
	v_or_b32_e32 v29, 16, v146
	v_lshl_add_u32 v190, v29, 2, 0
	v_add_u32_e32 v29, 0x24800, v190
	ds_read_b128 v[30:33], v29
	v_mov_b32_e32 v196, v127
	v_mov_b32_e32 v197, v127
	v_add_u32_e32 v29, 0x24900, v190
	ds_read_b128 v[116:119], v29
	s_waitcnt lgkmcnt(1)
	v_pk_add_f32 v[24:25], v[24:25], v[30:31]
	v_pk_add_f32 v[26:27], v[26:27], v[32:33]
	v_pk_mul_f32 v[24:25], v[24:25], s[4:5] op_sel_hi:[1,0]
	v_pk_mul_f32 v[26:27], v[26:27], s[4:5] op_sel_hi:[1,0]
	v_exp_f32_e32 v24, v24
	v_exp_f32_e32 v25, v25
	v_exp_f32_e32 v26, v26
	v_exp_f32_e32 v27, v27
	v_add_u32_e32 v29, 0x24c00, v190
	v_pk_add_f32 v[24:25], v[24:25], 1.0 op_sel_hi:[1,0]
	v_add_u32_e32 v80, 0x24b00, v190
	v_rcp_f32_e32 v24, v24
	v_rcp_f32_e32 v25, v25
	v_pk_add_f32 v[26:27], v[26:27], 1.0 op_sel_hi:[1,0]
	ds_read2_b64 v[36:39], v28 offset0:232 offset1:248
	ds_read2_b64 v[32:35], v28 offset0:198 offset1:216
	v_rcp_f32_e32 v26, v26
	v_pk_mul_f32 v[150:151], v[24:25], s[6:7] op_sel_hi:[1,0]
	v_rcp_f32_e32 v27, v27
	ds_read2_b64 v[100:103], v28 offset0:166 offset1:182
	v_mov_b32_dpp v196, v150 row_shr:1 row_mask:0xf bank_mask:0xf
	v_mov_b32_dpp v197, v151 row_shr:1 row_mask:0xf bank_mask:0xf
	v_pk_fma_f32 v[24:25], v[24:25], s[6:7], v[196:197] op_sel_hi:[1,0,1]
	v_mov_b32_e32 v196, v127
	v_mov_b32_e32 v197, v127
	v_pk_mul_f32 v[148:149], v[26:27], s[6:7] op_sel_hi:[1,0]
	v_add_f32_dpp v24, v24, v24 row_shr:2 row_mask:0xf bank_mask:0xf bound_ctrl:1
	v_add_f32_dpp v25, v25, v25 row_shr:2 row_mask:0xf bank_mask:0xf bound_ctrl:1
	ds_read_b128 v[28:31], v29
	ds_read_b128 v[108:111], v80
	v_add_f32_dpp v24, v24, v24 row_shr:4 row_mask:0xf bank_mask:0xf bound_ctrl:1
	v_add_f32_dpp v25, v25, v25 row_shr:4 row_mask:0xf bank_mask:0xf bound_ctrl:1
	v_add_u32_e32 v80, 0x24d00, v190
	v_mov_b32_dpp v196, v148 row_shr:1 row_mask:0xf bank_mask:0xf
	v_mov_b32_dpp v197, v149 row_shr:1 row_mask:0xf bank_mask:0xf
	v_add_f32_dpp v24, v24, v24 row_shr:8 row_mask:0xf bank_mask:0xf bound_ctrl:1
	v_add_f32_dpp v25, v25, v25 row_shr:8 row_mask:0xf bank_mask:0xf bound_ctrl:1
	v_add_u32_e32 v81, 0x24e00, v190
	v_pk_fma_f32 v[26:27], v[26:27], s[6:7], v[196:197] op_sel_hi:[1,0,1]
	ds_read_b128 v[112:115], v80
	ds_read_b128 v[104:107], v81
	v_add_u32_e32 v80, 0x24a00, v190
	v_add_u32_e32 v81, 0x24f00, v190
	v_add_f32_dpp v26, v26, v26 row_shr:2 row_mask:0xf bank_mask:0xf bound_ctrl:1
	v_add_f32_dpp v27, v27, v27 row_shr:2 row_mask:0xf bank_mask:0xf bound_ctrl:1
	ds_read_b128 v[88:91], v80
	ds_read_b128 v[80:83], v81
	v_add_f32_dpp v26, v26, v26 row_shr:4 row_mask:0xf bank_mask:0xf bound_ctrl:1
	v_add_f32_dpp v27, v27, v27 row_shr:4 row_mask:0xf bank_mask:0xf bound_ctrl:1
	s_nop 0
	v_add_f32_dpp v26, v26, v26 row_shr:8 row_mask:0xf bank_mask:0xf bound_ctrl:1
	v_add_f32_dpp v27, v27, v27 row_shr:8 row_mask:0xf bank_mask:0xf bound_ctrl:1
; __device__ __forceinline__ f32x4 ld_bf4(const bf16_t* p) { const u32x2 u = *(const u32x2*)p; return (f32x4){bf_lo(u.x), bf_hi(u.x), bf_lo(u.y), bf_hi(u.y)}; }
; #define LDS_BARRIER() do { asm volatile("s_waitcnt lgkmcnt(0)" ::: "memory"); __builtin_amdgcn_s_barrier(); asm volatile("" ::: "memory"); } while (0)
; __device__ __forceinline__ void phase_prep(const Params& p, unsigned char* shm) {
;     ...
;                 { const f32x4 vc = ld_bf4(zc + 128 + c4), vp = ld_bf4(zp + 128 + c4); vm[n] = vc + *(const f32x4*)(prm + 256 + c4) * (vp - vc); }
;                 const f32x4 kc = ld_bf4(zc + 64 + c4), kpv = ld_bf4(zp + 64 + c4);
;                 const f32x4 k = kc + *(const f32x4*)(prm + 192 + c4) * (kpv - kc);
;                 kkv[n] = k * *(const f32x4*)(prm + 320 + c4);
;                 kp[n] = k * (1.0f + (av[n] - 1.0f) * *(const f32x4*)(prm + 384 + c4));
;                 const f32x4 rc = ld_bf4(zc + c4), rp = ld_bf4(zp + c4);
;                 rm[n] = rc + *(const f32x4*)(prm + 128 + c4) * (rp - rc);
;                 const f32x4 rkw = rm[n] * kp[n] * *(const f32x4*)(prm + 448 + c4);
;                 { const f32x4 sq = kkv[n] * kkv[n]; nrm += (sq[0] + sq[1]) + (sq[2] + sq[3]); }
;                 rk += rkw[0] + rkw[1] + rkw[2] + rkw[3];
; #pragma unroll
;                 for (int j = 0; j < 4; ++j) {
;                     float x = lw[n][j];
;                     x += __int_as_float(__builtin_amdgcn_update_dpp(0, __float_as_int(x), 0x111, 0xf, 0xf, false));
;                     x += __int_as_float(__builtin_amdgcn_update_dpp(0, __float_as_int(x), 0x112, 0xf, 0xf, false));
;                     x += __int_as_float(__builtin_amdgcn_update_dpp(0, __float_as_int(x), 0x114, 0xf, 0xf, false));
;                     x += __int_as_float(__builtin_amdgcn_update_dpp(0, __float_as_int(x), 0x118, 0xf, 0xf, false));
;                     cs[n][j] = x;
;                 }
;                 if (fr == 15) *(f32x4*)(tot + tt * 64 + c4) = cs[n];
;             }
;             nrm += __shfl_xor(nrm, 16); nrm += __shfl_xor(nrm, 32);
;             rk += __shfl_xor(rk, 16); rk += __shfl_xor(rk, 32);
;             if (fq == 0) { red[wid * 16 + fr] = nrm; red[128 + wid * 16 + fr] = rk; }
;         }
;         LDS_BARRIER();
	s_and_saveexec_b64 s[20:21], s[18:19]
	ds_write_b128 v191, v[24:27] offset:64
	s_or_b64 exec, exec, s[20:21]
	v_pk_add_f32 v[74:75], v[74:75], v[86:87]
	v_pk_add_f32 v[72:73], v[72:73], v[84:85]
	v_pk_mul_f32 v[74:75], v[74:75], s[4:5] op_sel_hi:[1,0]
	v_pk_mul_f32 v[72:73], v[72:73], s[4:5] op_sel_hi:[1,0]
	v_exp_f32_e32 v74, v74
	v_exp_f32_e32 v75, v75
	v_exp_f32_e32 v72, v72
	v_exp_f32_e32 v73, v73
	v_lshlrev_b32_e32 v84, 16, v52
	v_pk_add_f32 v[74:75], v[74:75], 1.0 op_sel_hi:[1,0]
	v_and_b32_e32 v85, 0xffff0000, v52
	v_pk_add_f32 v[72:73], v[72:73], 1.0 op_sel_hi:[1,0]
	v_rcp_f32_e32 v74, v74
	v_rcp_f32_e32 v75, v75
	v_rcp_f32_e32 v72, v72
	v_rcp_f32_e32 v73, v73
	v_lshlrev_b32_e32 v52, 16, v53
	v_and_b32_e32 v53, 0xffff0000, v53
	v_lshlrev_b32_e32 v86, 16, v70
	v_and_b32_e32 v87, 0xffff0000, v70
	v_lshlrev_b32_e32 v70, 16, v71
	v_and_b32_e32 v71, 0xffff0000, v71
	v_sub_f32_e32 v71, v71, v53
	v_sub_f32_e32 v70, v70, v52
	v_pk_fma_f32 v[52:53], v[94:95], v[70:71], v[52:53]
	v_pk_add_f32 v[94:95], v[74:75], -1.0 op_sel_hi:[1,0]
	v_sub_f32_e32 v87, v87, v85
	v_sub_f32_e32 v86, v86, v84
	v_pk_add_f32 v[70:71], v[72:73], -1.0 op_sel_hi:[1,0]
	v_pk_fma_f32 v[78:79], v[78:79], v[94:95], 1.0 op_sel_hi:[1,1,0]
	v_pk_fma_f32 v[92:93], v[92:93], v[86:87], v[84:85]
	v_pk_mul_f32 v[84:85], v[98:99], v[52:53]
	v_pk_fma_f32 v[70:71], v[76:77], v[70:71], 1.0 op_sel_hi:[1,1,0]
	v_pk_mul_f32 v[76:77], v[52:53], v[78:79]
	v_lshlrev_b32_e32 v52, 16, v50
	v_and_b32_e32 v53, 0xffff0000, v50
	v_lshlrev_b32_e32 v78, 16, v68
	v_and_b32_e32 v68, 0xffff0000, v68
	v_pk_mul_f32 v[86:87], v[96:97], v[92:93]
	v_pk_mul_f32 v[70:71], v[92:93], v[70:71]
	v_lshlrev_b32_e32 v50, 16, v51
	v_and_b32_e32 v51, 0xffff0000, v51
	v_lshlrev_b32_e32 v92, 16, v69
	v_and_b32_e32 v79, 0xffff0000, v69
	v_sub_f32_e32 v69, v68, v53
	v_sub_f32_e32 v68, v78, v52
	v_sub_f32_e32 v79, v79, v51
	v_sub_f32_e32 v78, v92, v50
	v_pk_fma_f32 v[64:65], v[64:65], v[68:69], v[52:53]
	v_pk_fma_f32 v[66:67], v[66:67], v[78:79], v[50:51]
	v_pk_mul_f32 v[50:51], v[70:71], v[64:65]
	v_pk_mul_f32 v[52:53], v[76:77], v[66:67]
	v_pk_mul_f32 v[50:51], v[60:61], v[50:51]
	v_pk_mul_f32 v[52:53], v[62:63], v[52:53]
	v_add_f32_e32 v50, v50, v51
	v_add_f32_e32 v50, v52, v50
	v_add_f32_e32 v50, v53, v50
	v_add_f32_e32 v93, 0, v50
	s_waitcnt lgkmcnt(9)
	v_pk_add_f32 v[50:51], v[58:59], v[118:119]
	v_pk_add_f32 v[52:53], v[56:57], v[116:117]
	v_pk_mul_f32 v[50:51], v[50:51], s[4:5] op_sel_hi:[1,0]
	v_pk_mul_f32 v[52:53], v[52:53], s[4:5] op_sel_hi:[1,0]
	v_exp_f32_e32 v56, v50
	v_exp_f32_e32 v52, v52
	v_exp_f32_e32 v53, v53
	v_exp_f32_e32 v57, v51
	v_pk_mul_f32 v[60:61], v[84:85], v[84:85]
	v_pk_mul_f32 v[62:63], v[86:87], v[86:87]
	v_pk_add_f32 v[50:51], v[52:53], 1.0 op_sel_hi:[1,0]
	v_pk_add_f32 v[52:53], v[56:57], 1.0 op_sel_hi:[1,0]
	v_rcp_f32_e32 v50, v50
	v_rcp_f32_e32 v51, v51
	v_rcp_f32_e32 v52, v52
	v_rcp_f32_e32 v53, v53
	v_add_f32_e32 v62, v62, v63
	v_add_f32_e32 v60, v60, v61
	s_waitcnt lgkmcnt(8)
	v_lshlrev_b32_e32 v56, 16, v36
	v_and_b32_e32 v57, 0xffff0000, v36
	v_lshlrev_b32_e32 v36, 16, v37
	v_and_b32_e32 v37, 0xffff0000, v37
	s_waitcnt lgkmcnt(6)
	v_lshlrev_b32_e32 v58, 16, v103
	v_and_b32_e32 v59, 0xffff0000, v103
	v_add_f32_e32 v92, v62, v60
	v_lshlrev_b32_e32 v60, 16, v102
	v_and_b32_e32 v61, 0xffff0000, v102
	v_sub_f32_e32 v59, v59, v37
	v_sub_f32_e32 v58, v58, v36
	v_sub_f32_e32 v61, v61, v57
	v_sub_f32_e32 v60, v60, v56
	s_waitcnt lgkmcnt(4)
	v_pk_fma_f32 v[62:63], v[110:111], v[58:59], v[36:37]
	v_pk_add_f32 v[36:37], v[50:51], -1.0 op_sel_hi:[1,0]
	v_pk_add_f32 v[68:69], v[52:53], -1.0 op_sel_hi:[1,0]
	v_pk_fma_f32 v[56:57], v[108:109], v[60:61], v[56:57]
	s_waitcnt lgkmcnt(2)
	v_pk_fma_f32 v[68:69], v[106:107], v[68:69], 1.0 op_sel_hi:[1,1,0]
	v_pk_fma_f32 v[36:37], v[104:105], v[36:37], 1.0 op_sel_hi:[1,1,0]
	v_pk_mul_f32 v[58:59], v[114:115], v[62:63]
	v_pk_mul_f32 v[60:61], v[112:113], v[56:57]
	v_pk_mul_f32 v[36:37], v[56:57], v[36:37]
	v_pk_mul_f32 v[56:57], v[62:63], v[68:69]
	v_lshlrev_b32_e32 v62, 16, v34
	v_and_b32_e32 v63, 0xffff0000, v34
	v_lshlrev_b32_e32 v34, 16, v35
	v_and_b32_e32 v35, 0xffff0000, v35
	v_lshlrev_b32_e32 v68, 16, v100
	v_and_b32_e32 v69, 0xffff0000, v100
	v_lshlrev_b32_e32 v78, 16, v101
	v_and_b32_e32 v79, 0xffff0000, v101
	v_sub_f32_e32 v69, v69, v63
	v_sub_f32_e32 v68, v68, v62
	v_sub_f32_e32 v79, v79, v35
	v_sub_f32_e32 v78, v78, v34
	s_waitcnt lgkmcnt(1)
	v_pk_fma_f32 v[34:35], v[90:91], v[78:79], v[34:35]
	v_pk_fma_f32 v[62:63], v[88:89], v[68:69], v[62:63]
	v_pk_mul_f32 v[78:79], v[56:57], v[34:35]
	v_pk_mul_f32 v[68:69], v[36:37], v[62:63]
	s_waitcnt lgkmcnt(0)
	v_pk_mul_f32 v[78:79], v[82:83], v[78:79]
	v_pk_mul_f32 v[68:69], v[80:81], v[68:69]
	v_pk_mul_f32 v[80:81], v[58:59], v[58:59]
	v_pk_mul_f32 v[82:83], v[60:61], v[60:61]
	v_add_f32_e32 v80, v80, v81
	v_add_f32_e32 v82, v82, v83
	v_add_f32_e32 v80, v82, v80
	v_and_b32_e32 v82, 64, v180
	v_xor_b32_e32 v81, 16, v180
	v_add_u32_e32 v82, 64, v82
	v_add_f32_e32 v68, v68, v69
	v_cmp_lt_i32_e32 vcc, v81, v82
	v_add_f32_e32 v68, v78, v68
	v_add_f32_e32 v68, v79, v68
	v_cndmask_b32_e32 v81, v180, v81, vcc
	v_add_f32_e32 v80, v92, v80
	v_lshlrev_b32_e32 v81, 2, v81
	v_add_f32_e32 v68, v93, v68
	ds_bpermute_b32 v83, v81, v80
	ds_bpermute_b32 v79, v81, v68
	v_xor_b32_e32 v78, 32, v180
	v_cmp_lt_i32_e32 vcc, v78, v82
	s_ashr_i32 s71, s25, 6
	s_waitcnt lgkmcnt(1)
	v_add_f32_e32 v69, v80, v83
	v_cndmask_b32_e32 v78, v180, v78, vcc
	v_lshlrev_b32_e32 v78, 2, v78
	s_waitcnt lgkmcnt(0)
	v_add_f32_e32 v79, v68, v79
	ds_bpermute_b32 v80, v78, v69
	ds_bpermute_b32 v81, v78, v79
	v_and_b32_e32 v68, 63, v187
	s_ashr_i32 s27, s26, 31
	v_cmp_gt_u32_e32 vcc, 16, v68
	s_waitcnt lgkmcnt(1)
	v_add_f32_e32 v78, v69, v80
	s_waitcnt lgkmcnt(0)
	v_add_f32_e32 v69, v79, v81
	s_lshl_b32 s72, s71, 4
	s_and_saveexec_b64 s[20:21], vcc
	s_lshl_b32 s23, s72, 2
	s_add_i32 s23, s23, 0
	v_lshl_add_u32 v79, v185, 2, s23
	v_add_u32_e32 v79, 0x1b000, v79
	ds_write2st64_b32 v79, v78, v69 offset1:2
	s_or_b64 exec, exec, s[20:21]
	s_xor_b32 s20, s72, 64
	s_lshl_b32 s20, s20, 2
	s_add_i32 s20, s20, 0
	v_lshl_add_u32 v81, v185, 2, s20
	s_waitcnt lgkmcnt(0)
	s_barrier
; __device__ __forceinline__ void st_bf4(bf16_t* p, f32x4 v) { u32x2 u; u.x = pk_bf16(v[0], v[1]); u.y = pk_bf16(v[2], v[3]); *(u32x2*)p = u; }
; __device__ __forceinline__ void phase_prep(const Params& p, unsigned char* shm) {
;     ...
;         {
;             nrm += red[(wid ^ 4) * 16 + fr]; rk += red[128 + (wid ^ 4) * 16 + fr];
;             const float inv = 1.0f / fmaxf(sqrtf(nrm), 1e-12f);
;             p.PRK[(size_t)row * 16 + h] = rk;
; #pragma unroll
;             for (int n = 0; n < 2; ++n) {
;                 const int c4 = 32 * chh + 16 * n + 4 * fq;
;                 f32x4 pre = (f32x4){0.f, 0.f, 0.f, 0.f}, total = (f32x4){0.f, 0.f, 0.f, 0.f};
; #pragma unroll
;                 for (int t2 = 0; t2 < 4; ++t2) { const f32x4 x = *(const f32x4*)(tot + t2 * 64 + c4); total += x; if (t2 < tt) pre += x; }
;                 const f32x4 csum = pre + cs[n];
;                 f32x4 eg, eng, egm, etc; const f32x4 ncs = -csum, cml = csum - lw[n], tmc = total - csum;
; #pragma unroll
;                 for (int j = 0; j < 4; ++j) { eg[j] = __builtin_amdgcn_exp2f(csum[j]); eng[j] = __builtin_amdgcn_exp2f(ncs[j]); egm[j] = __builtin_amdgcn_exp2f(cml[j]); etc[j] = __builtin_amdgcn_exp2f(tmc[j]); }
;                 const f32x4 kkn = kkv[n] * inv, bb = kkn * av[n];
;                 const f32x4 qt = rm[n] * eg, kt = kp[n] * eng, bt = bb * eng, kkt = kkn * egm, kpp = kp[n] * etc, bpp = bb * etc;
;                 st_bf4(Qt + tk * LD + c4, qt); st_bf4(Kt + tk * LD + c4, kt); st_bf4(Bt + tk * LD + c4, bt);
;                 const u32x2 kkw = pk_bf4(kkt), vmw = pk_bf4(vm[n]), kpw = pk_bf4(kpp), bpw = pk_bf4(bpp);
;                 *(u32x2*)(KKt + tk * LD + c4) = kkw;
;                 { bf16_t* d = KKtT + c4 * LD + tk; d[0] = (bf16_t)kkw.x; d[LD] = (bf16_t)(kkw.x >> 16); d[2 * LD] = (bf16_t)kkw.y; d[3 * LD] = (bf16_t)(kkw.y >> 16); }
;                 { bf16_t* d = VmT + c4 * LD + tk; d[0] = (bf16_t)vmw.x; d[LD] = (bf16_t)(vmw.x >> 16); d[2 * LD] = (bf16_t)vmw.y; d[3 * LD] = (bf16_t)(vmw.y >> 16); }
;                 { bf16_t* d = KpT + c4 * LD + tk; d[0] = (bf16_t)kpw.x; d[LD] = (bf16_t)(kpw.x >> 16); d[2 * LD] = (bf16_t)kpw.y; d[3 * LD] = (bf16_t)(kpw.y >> 16); }
;                 { bf16_t* d = BpT + c4 * LD + tk; d[0] = (bf16_t)bpw.x; d[LD] = (bf16_t)(bpw.x >> 16); d[2 * LD] = (bf16_t)bpw.y; d[3 * LD] = (bf16_t)(bpw.y >> 16); }
	v_add_u32_e32 v81, 0x1b000, v81
	ds_read2st64_b32 v[88:89], v81 offset1:2
	v_and_b32_e32 v83, 0xffff0000, v54
	v_lshlrev_b32_e32 v79, 16, v48
	v_and_b32_e32 v48, 0xffff0000, v48
	v_lshlrev_b32_e32 v81, 16, v49
	v_and_b32_e32 v90, 0xffff0000, v49
	v_sub_f32_e32 v49, v48, v83
	s_waitcnt lgkmcnt(0)
	v_add_f32_e32 v48, v78, v88
	v_mul_f32_e32 v78, 0x4f800000, v48
	v_cmp_gt_f32_e32 vcc, s53, v48
	v_lshlrev_b32_e32 v82, 16, v54
	v_lshlrev_b32_e32 v54, 16, v55
	v_cndmask_b32_e32 v88, v48, v78, vcc
	v_sqrt_f32_e32 v91, v88
	v_and_b32_e32 v55, 0xffff0000, v55
	v_sub_f32_e32 v78, v81, v54
	v_sub_f32_e32 v48, v79, v82
	v_add_u32_e32 v81, -1, v91
	v_sub_f32_e32 v79, v90, v55
	v_fma_f32 v90, -v81, v91, v88
	v_cmp_ge_f32_e64 s[20:21], 0, v90
	v_add_u32_e32 v90, 1, v91
	v_pk_fma_f32 v[82:83], v[44:45], v[48:49], v[82:83]
	v_cndmask_b32_e64 v81, v91, v81, s[20:21]
	v_fma_f32 v91, -v90, v91, v88
	v_cmp_lt_f32_e64 s[20:21], 0, v91
	v_pk_fma_f32 v[54:55], v[46:47], v[78:79], v[54:55]
	v_or_b32_e32 v80, s24, v126
	v_cndmask_b32_e64 v81, v81, v90, s[20:21]
	v_mul_f32_e32 v90, 0x37800000, v81
	v_cndmask_b32_e32 v81, v81, v90, vcc
	v_cmp_class_f32_e32 vcc, v88, v181
	s_lshl_b32 s40, s22, 2
	v_add_f32_e32 v45, v69, v89
	v_cndmask_b32_e32 v81, v81, v88, vcc
	v_max_f32_e32 v81, 0x2b8cbccc, v81
	v_div_scale_f32 v88, s[20:21], v81, v81, 1.0
	v_rcp_f32_e32 v90, v88
	s_mov_b64 s[20:21], s[92:93]
	s_cmp_eq_u32 s28, 0
	s_cselect_b64 s[24:25], -1, 0
	v_fma_f32 v44, -v88, v90, 1.0
	v_fmac_f32_e32 v90, v44, v90
	v_div_scale_f32 v44, vcc, 1.0, v81, 1.0
	v_mul_f32_e32 v46, v44, v90
	v_fma_f32 v47, -v88, v46, v44
	v_fmac_f32_e32 v46, v47, v90
	v_fma_f32 v44, -v88, v46, v44
	v_div_fmas_f32 v44, v44, v90, v46
	v_div_fixup_f32 v44, v44, v81, 1.0
	v_ashrrev_i32_e32 v81, 31, v80
	v_lshlrev_b64 v[46:47], 6, v[80:81]
	s_waitcnt lgkmcnt(0)
	v_lshl_add_u64 v[46:47], s[20:21], 0, v[46:47]
	v_lshl_add_u64 v[46:47], v[46:47], 0, s[40:41]
	global_store_dword v[46:47], v45, off
	v_lshl_add_u32 v46, v146, 2, 0
	v_add_u32_e32 v69, 0x1b400, v46
	ds_read_b128 v[46:49], v69
	ds_read_b128 v[78:81], v69 offset:256
	s_lshl_b64 s[22:23], s[26:27], 8
	s_cmp_gt_u32 s28, 1
	ds_read_b128 v[88:91], v69 offset:512
	s_waitcnt lgkmcnt(2)
	v_pk_add_f32 v[48:49], v[48:49], 0 op_sel_hi:[1,0]
	s_cselect_b64 vcc, -1, 0
	v_cndmask_b32_e64 v93, v49, 0, s[24:25]
	v_cndmask_b32_e64 v92, v48, 0, s[24:25]
	s_waitcnt lgkmcnt(1)
	v_pk_add_f32 v[94:95], v[80:81], v[92:93]
	v_pk_add_f32 v[46:47], v[46:47], 0 op_sel_hi:[1,0]
	v_cndmask_b32_e32 v97, v93, v95, vcc
	v_cndmask_b32_e32 v96, v92, v94, vcc
	ds_read_b128 v[92:95], v69 offset:768
	v_cndmask_b32_e64 v101, v47, 0, s[24:25]
	v_cndmask_b32_e64 v100, v46, 0, s[24:25]
	v_pk_add_f32 v[46:47], v[46:47], v[78:79]
	v_pk_add_f32 v[78:79], v[78:79], v[100:101]
	s_cmp_eq_u32 s28, 3
	v_cndmask_b32_e32 v79, v101, v79, vcc
	v_cndmask_b32_e32 v78, v100, v78, vcc
	s_waitcnt lgkmcnt(1)
	v_pk_add_f32 v[98:99], v[90:91], v[96:97]
	s_cselect_b64 s[20:21], -1, 0
	v_pk_add_f32 v[48:49], v[48:49], v[80:81]
	v_pk_add_f32 v[80:81], v[46:47], v[88:89]
	v_pk_add_f32 v[46:47], v[88:89], v[78:79]
	v_pk_add_f32 v[48:49], v[48:49], v[90:91]
	v_cndmask_b32_e64 v89, v97, v99, s[20:21]
	v_cndmask_b32_e64 v88, v96, v98, s[20:21]
	v_cndmask_b32_e64 v79, v79, v47, s[20:21]
	v_cndmask_b32_e64 v78, v78, v46, s[20:21]
	s_waitcnt lgkmcnt(0)
	v_pk_add_f32 v[46:47], v[48:49], v[94:95]
	v_pk_add_f32 v[48:49], v[80:81], v[92:93]
	v_pk_add_f32 v[42:43], v[42:43], v[88:89]
	v_pk_add_f32 v[40:41], v[40:41], v[78:79]
	v_sub_f32_e32 v91, v46, v42
	v_sub_f32_e32 v79, v48, v40
	v_sub_f32_e32 v69, v47, v43
	v_sub_f32_e32 v89, v49, v41
	v_exp_f32_e32 v78, v40
	v_exp_f32_e64 v80, -v40
	v_sub_f32_e32 v40, v40, v154
	v_exp_f32_e32 v88, v79
	v_exp_f32_e32 v79, v41
	v_exp_f32_e64 v81, -v41
	v_sub_f32_e32 v41, v41, v155
	v_exp_f32_e32 v90, v42
	v_exp_f32_e64 v92, -v42
	v_sub_f32_e32 v42, v42, v152
	v_exp_f32_e32 v94, v91
	v_exp_f32_e32 v91, v43
	v_exp_f32_e64 v93, -v43
	v_sub_f32_e32 v43, v43, v153
	v_mul_u32_u24_e32 v45, 0x48, v126
	v_exp_f32_e32 v40, v40
	v_exp_f32_e32 v41, v41
	v_exp_f32_e32 v42, v42
	v_exp_f32_e32 v43, v43
	v_lshlrev_b32_e32 v45, 1, v45
	v_pk_mul_f32 v[84:85], v[84:85], v[44:45] op_sel_hi:[1,0]
	v_pk_mul_f32 v[86:87], v[86:87], v[44:45] op_sel_hi:[1,0]
	v_exp_f32_e32 v89, v89
	v_pk_mul_f32 v[72:73], v[72:73], v[86:87]
	v_pk_mul_f32 v[74:75], v[74:75], v[84:85]
	v_pk_mul_f32 v[66:67], v[66:67], v[90:91]
	v_pk_mul_f32 v[64:65], v[64:65], v[78:79]
	v_pk_mul_f32 v[78:79], v[76:77], v[92:93]
	v_pk_mul_f32 v[90:91], v[70:71], v[80:81]
	v_exp_f32_e32 v95, v69
	v_pk_mul_f32 v[92:93], v[74:75], v[92:93]
	v_pk_mul_f32 v[80:81], v[72:73], v[80:81]
	v_pk_mul_f32 v[42:43], v[84:85], v[42:43]
	v_pk_mul_f32 v[84:85], v[86:87], v[40:41]
	v_add3_u32 v40, 0, v45, v147
	v_cvt_pk_bf16_f32 v64, v64, v65
	v_cvt_pk_bf16_f32 v65, v66, v67
	v_cvt_pk_bf16_f32 v66, v90, v91
	v_cvt_pk_bf16_f32 v67, v78, v79
	ds_write2st64_b64 v40, v[64:65], v[66:67] offset0:72 offset1:90
	v_cvt_pk_bf16_f32 v64, v80, v81
	v_cvt_pk_bf16_f32 v65, v92, v93
	v_cvt_pk_bf16_f32 v66, v84, v85
	v_cvt_pk_bf16_f32 v67, v42, v43
	v_lshlrev_b32_e32 v102, 1, v126
	ds_write2st64_b64 v40, v[64:65], v[66:67] offset0:108 offset1:126
	v_mul_u32_u24_e32 v64, s50, v146
	v_pk_mul_f32 v[70:71], v[70:71], v[88:89]
	v_pk_mul_f32 v[72:73], v[72:73], v[88:89]
	v_cvt_pk_bf16_f32 v41, v82, v83
	v_add3_u32 v42, s55, v102, v64
	v_add3_u32 v43, s56, v102, v64
	s_cmp_lg_u32 s28, 0
	v_pk_mul_f32 v[76:77], v[76:77], v[94:95]
	v_pk_mul_f32 v[74:75], v[74:75], v[94:95]
	v_cvt_pk_bf16_f32 v45, v54, v55
	v_cvt_pk_bf16_f32 v55, v70, v71
	v_cvt_pk_bf16_f32 v70, v72, v73
	ds_write_b16 v42, v66
	ds_write_b16_d16_hi v42, v66 offset:144
	ds_write_b16 v42, v67 offset:288
	ds_write_b16_d16_hi v42, v67 offset:432
	ds_write_b16 v43, v41
	ds_write_b16_d16_hi v43, v41 offset:144
	ds_write_b16 v43, v45 offset:288
	ds_write_b16_d16_hi v43, v45 offset:432
	v_add3_u32 v54, s57, v102, v64
	v_add3_u32 v41, s58, v102, v64
	v_cvt_pk_bf16_f32 v69, v76, v77
	v_cvt_pk_bf16_f32 v71, v74, v75
	ds_write_b16 v54, v55
	ds_write_b16_d16_hi v54, v55 offset:144
	ds_write_b16 v54, v69 offset:288
	ds_write_b16_d16_hi v54, v69 offset:432
	ds_write_b16 v41, v70
	ds_write_b16_d16_hi v41, v70 offset:144
	ds_write_b16 v41, v71 offset:288
	ds_write_b16_d16_hi v41, v71 offset:432
	s_cbranch_scc1 .LBB0_197
	s_mov_b64 s[30:31], s[94:95]
	v_exp_f32_e32 v64, v48
	v_exp_f32_e32 v65, v49
	v_exp_f32_e32 v66, v46
	v_exp_f32_e32 v67, v47
	s_waitcnt lgkmcnt(0)
	s_add_u32 s30, s30, s22
	v_ashrrev_i32_e32 v147, 31, v146
	s_addc_u32 s31, s31, s23
	v_lshl_add_u64 v[46:47], v[146:147], 2, s[30:31]
	global_store_dwordx4 v[46:47], v[64:67], off

; __device__ __forceinline__ unsigned xb_add(unsigned* p, unsigned v) { return __hip_atomic_fetch_add(p, v, __ATOMIC_RELAXED, __HIP_MEMORY_SCOPE_AGENT); }
; #define P() (*(const Params*)(cp = cp_launder(cp)))
; __device__ __forceinline__ void xcd_barrier(XcdBarrier& b) {
;     asm volatile("s_waitcnt vmcnt(0)" ::: "memory");
;     __syncthreads();
;     if (threadIdx.x == 0) {
;         unsigned* bar = b.bar;
;         __builtin_amdgcn_s_waitcnt(0);
;         if (b.nloc == 0u) xcd_barrier_complete(bar, b.x, b.nloc, b.nx);
;         const unsigned nloc = b.nloc, nx = b.nx;
;         const unsigned old = xb_add(&bar[XB_XSUB(b.x)], 1u);
;         const unsigned gen = old / nloc;
;         if (old + 1u == (gen + 1u) * nloc) {
; __global__ __launch_bounds__(512, 2) void k_mega(Params p) {
;     ...
;     phase_prep(P(), shm); xcd_barrier(xb);
.LBB0_280:
	s_waitcnt vmcnt(0)
	s_waitcnt lgkmcnt(0)
	s_cmp_lg_u32 s77, 0xc0
	s_cbranch_scc1 .Lprep_xb3
	s_mov_b32 s77, 1
	v_readlane_b32 s40, v244, 6
	v_readlane_b32 s41, v244, 7
	s_nop 3
	s_lshl_b32 s4, s40, 6
	s_nop 1
	v_writelane_b32 v244, s4, 8
	s_mov_b64 s[2:3], exec
	s_branch .LBB0_333
.Lprep_xb3:
	s_barrier
	s_mov_b64 s[2:3], exec
	v_readlane_b32 s4, v244, 1
	v_readlane_b32 s5, v244, 2
	s_and_b64 s[4:5], s[2:3], s[4:5]
	s_mov_b64 exec, s[4:5]
	s_cbranch_execz .LBB0_333
	v_cmp_eq_u32_e32 vcc, 0, v130
	s_waitcnt vmcnt(0) expcnt(0) lgkmcnt(0)
	s_and_saveexec_b64 s[4:5], vcc
	s_cbranch_execz .LBB0_296
	v_readlane_b32 s6, v244, 0
	s_mul_i32 s20, s39, s6
	s_add_u32 s6, s36, 0x1000
	s_addc_u32 s7, s37, 0
	s_add_u32 s8, s36, 0x1100
	s_addc_u32 s9, s37, 0
	s_add_u32 s10, s36, 0x1200
	s_addc_u32 s11, s37, 0
	s_add_u32 s12, s36, 0x1300
	s_mul_i32 s20, s20, s38
	s_addc_u32 s13, s37, 0
	s_mov_b32 s21, 1
	v_mov_b32_e32 v16, 0
	s_branch .LBB0_284

; __device__ __forceinline__ void seq_item(const Params& p, unsigned char* shm, int row0, int nchunks, int h, const float* S0, float* Sout) {
;     constexpr int LD = 72, SLOT = 4 * 64 * LD + 128;
;     bf16_t* Sb = (bf16_t*)shm; bf16_t* UT = Sb + 64 * LD; bf16_t* ring = UT + 64 * LD;
;     const int tid = threadIdx.x, lane = tid & 63, wid = tid >> 6, fr = lane & 15, fq = lane >> 4;
;     const int m = wid >> 1, nv0 = 2 * (wid & 1), c0 = 16 * m + 4 * fq;
;     const int crow = tid >> 3, cseg = (tid & 7) * 8;
; __device__ __forceinline__ void phase_mix(const Params& p, unsigned char* shm) {
;     constexpr int NSCAN_P = 64, NSCAN_S = 512, NSGU = 2 * (MT / 128);
;     const int b = blockIdx.x, G = gridDim.x;
;     if (G >= 128) {
;         if (b < NSCAN_P) { const int sb = b >> 4, h = b & 15; seq_item(p, shm, sb * SEQ, SEQ / 64, h, nullptr, p.out + O_WKVP + (size_t)(sb * 16 + h) * 4096); return; }
;         const int nb = G - NSCAN_P, c = b - NSCAN_P;
;         for (int it = c; it < NSCAN_S + NSGU; it += nb) {
;             if (it < NSCAN_S) { const int sb = it >> 4, h = it & 15; seq_item(p, shm, MP + sb * DSEQ, 1, h, p.st_wkv + (size_t)(sb * 16 + h) * 4096, p.out + O_WKVS + (size_t)(sb * 16 + h) * 4096); }
;             else sgu_item(p, shm, (it - NSCAN_S) >> 1, ((it - NSCAN_S) & 1) * 4);
.LBB0_333:
	s_or_b64 exec, exec, s[2:3]
	s_cmp_lg_u32 s77, 0x100
	s_cbranch_scc1 .Lmix_go
	s_cmp_lt_u32 s40, 64
	s_cbranch_scc1 .Lmix_go
	s_movk_i32 s77, 0xc0
	s_movk_i32 s32, 0x2200
	s_add_i32 s40, s40, 0x1fc0
	s_branch .Lprep_re
.Lmix_go:
	s_cmpk_gt_i32 s38, 0x7f
	s_mov_b64 s[2:3], -1
	s_barrier
	s_cbranch_scc1 .LBB0_389
	s_cmpk_gt_i32 s40, 0x45f
	s_cbranch_scc1 .LBB0_388
	s_waitcnt vmcnt(2)
	v_bfe_u32 v2, v133, 6, 1
	s_waitcnt vmcnt(0)
	v_lshl_or_b32 v8, v2, 6, v161
	s_movk_i32 s2, 0x110
	v_mov_b32_e32 v20, 0x1100
	v_mad_u32_u24 v20, v169, s2, v20
	v_mad_u32_u24 v115, v8, s2, 0
	v_cmp_lt_u32_e64 s[2:3], 15, v133
	v_and_b32_e32 v54, 56, v131
	v_mul_u32_u24_e32 v25, 0x48, v164
	v_writelane_b32 v244, s2, 9
	v_lshlrev_b32_e32 v117, 1, v25
	v_lshlrev_b32_e32 v25, 1, v54
	v_writelane_b32 v244, s3, 10
	s_add_i32 s2, 0, 0x12100
	v_add3_u32 v122, s2, v117, v25
	s_add_i32 s2, 0, 0x14500
	v_lshlrev_b32_e32 v26, 2, v134
	v_add3_u32 v124, s2, v117, v25
	s_add_i32 s2, 0, 0x16900
	v_add_u32_e32 v125, s2, v26
	s_add_i32 s2, 0, 0x16a00
	v_add3_u32 v140, s2, v117, v25
	s_add_i32 s2, 0, 0x18e00
	v_add3_u32 v141, s2, v117, v25
	s_add_i32 s2, 0, 0x1b200
	v_lshrrev_b32_e32 v5, 7, v133
	v_add3_u32 v142, s2, v117, v25
	s_add_i32 s2, 0, 0x1d600
	v_lshl_or_b32 v7, v5, 5, v161
	v_lshlrev_b32_e32 v2, 7, v2
	v_and_b32_e32 v23, 2, v169
	v_lshlrev_b32_e32 v8, 6, v161
	v_add3_u32 v143, s2, v117, v25
	s_add_i32 s2, 0, 0x1fa00
	v_and_b32_e32 v9, 48, v133
	v_add3_u32 v10, 0, v2, v158
	v_bitop3_b32 v2, v131, v123, 24 bitop3:0x6c
	v_add_u32_e32 v105, 32, v123
	v_mul_u32_u24_e32 v7, 0x110, v7
	v_lshl_or_b32 v52, v23, 10, v8
	v_lshl_or_b32 v23, v23, 4, v161
	v_add_u32_e32 v144, s2, v26
	v_readlane_b32 s2, v244, 8
	v_and_b32_e32 v1, 24, v131
	v_lshl_add_u32 v12, v2, 1, 0
	v_bitop3_b32 v2, v105, v131, 24 bitop3:0x78
	v_add_u32_e32 v107, 0x60, v123
	v_bfe_u32 v22, v133, 4, 2
	v_and_b32_e32 v24, 0x70, v164
	v_mul_u32_u24_e32 v126, 0x48, v23
	s_add_i32 s27, s2, 0xffff7000
	s_lshl_b32 s2, s38, 6
	v_add_u32_e32 v149, 1, v5
	v_add3_u32 v5, v7, v9, 0
	v_and_b32_e32 v51, 0x78, v131
	v_and_b32_e32 v53, 0x7c, v134
	v_lshl_add_u32 v15, v2, 1, 0
	v_or_b32_e32 v106, 64, v123
	v_bitop3_b32 v1, v123, v1, 64 bitop3:0x36
	v_bitop3_b32 v2, v107, v131, 24 bitop3:0x78
	v_add_u32_e32 v108, 16, v169
	v_or_b32_e32 v109, 32, v169
	v_lshl_or_b32 v50, v22, 2, v24
	v_lshl_add_u32 v23, v126, 1, 0
	v_or_b32_e32 v24, v24, v161
	v_writelane_b32 v244, s2, 11
	v_add_u32_e32 v150, 0x8c00, v5
	v_and_b32_e32 v5, 7, v133
	v_lshlrev_b32_e32 v0, 4, v171
	v_mov_b32_e32 v49, 0
	v_lshl_add_u32 v3, v53, 1, 0
	v_and_b32_e32 v55, 8, v133
	v_lshl_add_u32 v104, v51, 1, 0
	v_lshlrev_b32_e32 v11, 3, v123
	v_mul_u32_u24_e32 v13, 0x110, v51
	v_lshlrev_b32_e32 v14, 3, v105
	v_lshlrev_b32_e32 v16, 3, v106
	v_lshl_add_u32 v1, v1, 1, 0
	v_lshlrev_b32_e32 v17, 3, v107
	v_lshl_add_u32 v18, v2, 1, 0
	v_lshlrev_b32_e32 v2, 7, v169
	v_lshlrev_b32_e32 v4, 7, v108
	v_lshlrev_b32_e32 v6, 7, v109
	v_mul_u32_u24_e32 v19, 0x110, v169
	v_mul_u32_u24_e32 v21, 0x110, v105
	v_lshlrev_b32_e32 v8, 6, v164
	v_lshlrev_b32_e32 v27, 1, v50
	v_add_u32_e32 v28, 0x900, v23
	v_mul_u32_u24_e32 v137, 0x90, v24
	v_lshlrev_b32_e32 v24, 3, v22
	v_lshlrev_b32_e32 v22, 4, v22
	v_readlane_b32 s54, v244, 6
	v_lshlrev_b32_e32 v5, 4, v5
	s_mov_b32 s25, 0
	v_cmp_eq_u32_e64 s[8:9], 0, v171
	v_add_u32_e32 v110, 48, v169
	v_or_b32_e32 v111, 64, v169
	v_add_u32_e32 v112, 0x50, v169
	v_or_b32_e32 v113, 0x60, v169
	v_add_u32_e32 v114, 0x70, v169
	v_or_b32_e32 v116, 16, v55
	v_or_b32_e32 v56, v8, v54
	v_mov_b32_e32 v57, v49
	v_add3_u32 v118, 0, v117, v25
	v_cmp_gt_u32_e64 s[10:11], 16, v133
	v_add_u32_e32 v119, 0, v26
	v_add_u32_e32 v127, v23, v27
	v_add_u32_e32 v136, v28, v27
	v_add_u32_e32 v138, v23, v22
	v_add_u32_e32 v139, v28, v22
	v_add3_u32 v145, 0, v137, v22
	v_lshl_add_u32 v146, v50, 2, 0
	v_lshl_add_u32 v147, v170, 7, 0
	v_mul_u32_u24_e32 v148, 0x1d000, v170
	s_lshl_b32 s31, s54, 9
	s_lshl_b32 s2, s38, 9
	v_lshl_or_b32 v58, v164, 7, v5
	v_mov_b32_e32 v59, v49
	v_lshlrev_b32_e32 v60, 1, v0
	s_movk_i32 s41, 0x3a00
	s_mov_b32 s26, 0x3e6d3388
	s_mov_b32 s28, 0x3f07dc22
	s_mov_b32 s30, 0xbf3a00e3
	s_mov_b32 s34, 0x3f35f0e3
	s_mov_b32 s40, 0xbe11a98e
	s_mov_b32 s42, 0x3e027906
	s_mov_b32 s44, 0xbf38aa3b
	s_mov_b32 s58, 0x3a800000
	s_mov_b32 s43, 0x800000
	v_add_u32_e32 v151, 0, v11
	v_add_u32_e32 v152, v12, v13
	v_add_u32_e32 v153, 0, v14
	v_add_u32_e32 v154, v15, v13
	v_add_u32_e32 v155, 0, v16
	v_add_u32_e32 v156, v1, v13
	v_add_u32_e32 v157, 0, v17
	v_add_u32_e32 v172, v18, v13
	v_lshlrev_b32_e32 v62, 2, v2
	v_lshlrev_b32_e32 v64, 2, v4
	v_lshlrev_b32_e32 v66, 2, v6
	v_add_u32_e32 v173, v3, v19
	v_add_u32_e32 v174, v3, v20
	v_add_u32_e32 v175, v10, v7
	s_movk_i32 s45, 0x1000
	s_mov_b32 s50, 0xbfb8aa3b
	v_add_u32_e32 v176, v104, v21
	v_lshlrev_b32_e32 v68, 1, v8
	s_mov_b64 s[52:53], 0x40000
	v_mbcnt_hi_u32_b32 v177, -1, v129
	v_lshlrev_b32_e32 v178, 1, v24
	s_mov_b32 s51, s54
	v_readlane_b32 s55, v244, 7
	v_writelane_b32 v244, s2, 12
	s_branch .LBB0_337
